# DQK128 attention loop: waves 4-7 run the first half-step softmax cluster after the tile barrier instead of before it (half-step stagger of the VALU cluster)
# speedup vs baseline: 1.0076x; 1.0015x over previous
; #define LAS __attribute__((address_space(3)))
; __global__ void __launch_bounds__(NTHREADS, 2) fwd_kernel(Args a) {
;     extern __shared__ __attribute__((aligned(16))) unsigned char lds[];
;     LAS unsigned char* ldsl = (LAS unsigned char*)lds;
;     const int G = gridDim.x, bx = blockIdx.x;
;     ...
;     const int vcu = (G % 8 == 0) ? (bx % 8) * (G / 8) + bx / 8 : bx;
;     unsigned char* ws = a.ws;
_Z10fwd_kernel4Args:
	v_readfirstlane_b32 s100, v0
	s_load_dword s15, s[0:1], 0xd8
	s_load_dwordx2 s[94:95], s[0:1], 0xd0
	s_mov_b32 s14, s2
	s_add_u32 s2, s0, 0xd8
	s_addc_u32 s3, s1, 0
	v_writelane_b32 v252, s2, 0
	s_nop 1
	v_writelane_b32 v252, s3, 1
	s_waitcnt lgkmcnt(0)
	s_and_b32 s2, s15, 7
	s_cmp_lg_u32 s2, 0
	v_writelane_b32 v252, s14, 2
	s_cbranch_scc0 .LBB0_3
	s_cmpk_gt_i32 s95, 0x1000
	s_cbranch_scc1 .LBB0_4

; #define SBAR() __builtin_amdgcn_sched_barrier(0)
; #define DMA_K(t, buf) do { const char* kb_ = (const char*)Kh + (size_t)(t) * TILEB; \
;         glds16(kb_ + ksrc[0], (unsigned)__builtin_amdgcn_readfirstlane(lds0 + OFF_K + (buf) * SHM_K + (DQK == 128 ? widu * 2048 : widu * 1024))); \
;         if (DQK == 128) glds16(kb_ + ksrc[1], (unsigned)__builtin_amdgcn_readfirstlane(lds0 + OFF_K + (buf) * SHM_K + widu * 2048 + 1024)); } while (0)
; #define DMA_V(t, buf) do { const char* vb_ = (const char*)Vh + (size_t)(t) * TILEB; \
;         glds16(vb_ + vsrc[0], (unsigned)__builtin_amdgcn_readfirstlane(lds0 + (buf) * SHM_V + widu * 2048)); \
;         glds16(vb_ + vsrc[1], (unsigned)__builtin_amdgcn_readfirstlane(lds0 + (buf) * SHM_V + widu * 2048 + 1024)); } while (0)
; #define EXPH(P) do { _Pragma("unroll") for (int r = 0; r < 16; ++r) P[r] = __builtin_amdgcn_exp2f(P[r]); } while (0)
; template <int DQK, int NREG> __device__ __forceinline__ void qkt_mix(f32x16& p0, f32x16& p1, const char* Ks, const bf16x8* qr, const char* qs, int r32, int hi) {
;     p0 = f32x16{}; p1 = f32x16{};
; #pragma unroll
;     for (int d0 = 0; d0 < DQK / 16; ++d0) { const int cb = (d0 * 16 + hi * 8) * 2, ci = 0;
;         const bf16x8 b0 = *reinterpret_cast<const bf16x8*>(Ks + kswz<DQK>(r32, cb) + ci);
;         const bf16x8 b1 = *reinterpret_cast<const bf16x8*>(Ks + kswz<DQK>(r32, cb) + ci + 32 * (DQK * 2));
;         bf16x8 q; if (d0 < NREG) q = qr[d0]; else q = *reinterpret_cast<const bf16x8*>(qs + (d0 - NREG) * 1024);
;         p0 = __builtin_amdgcn_mfma_f32_32x32x16_bf16(b0, q, p0, 0, 0, 0);
;         p1 = __builtin_amdgcn_mfma_f32_32x32x16_bf16(b1, q, p1, 0, 0, 0); }
; }
;     ...
;         DMA_K(k + 1, 0); DMA_V(k, 1); SBAR();
;         if (isY) { EXPH(pA0); }
;         SBAR(); qkt_mix<DQK, NREG>(pB0, pB1, K_lds + SHM_K, qr, qs, r32, hi);
;         finishSM<true>(pA0, pA1, dummy_a, l_reg, pa0, pa1, pa2, pa3); SBAR();
;         pv_d0(o, vb0, pa0, pa1, pa2, pa3);
.LBB0_529:
	s_add_u32 s76, s44, 0xfffa0000
	s_addc_u32 s77, s45, -1
	v_lshl_add_u64 v[80:81], s[76:77], 0, v[160:161]
	s_mov_b32 s1, m0
	s_mov_b32 m0, s53
	s_nop 0
	global_load_lds_dwordx4 v[80:81], off
	s_mov_b32 m0, s1
	v_lshl_add_u64 v[80:81], s[76:77], 0, v[162:163]
	s_mov_b32 s1, m0
	s_mov_b32 m0, s54
	s_nop 0
	global_load_lds_dwordx4 v[80:81], off
	s_mov_b32 m0, s1
	s_cmp_lg_u32 0, -1
	s_cselect_b32 s1, 0, 0
	v_lshl_add_u64 v[200:201], s[44:45], 0, v[164:165]
	s_add_i32 s1, s1, s52
	v_lshl_add_u64 v[80:81], v[200:201], 0, s[20:21]
	s_add_i32 s75, s1, 0x4000
	s_mov_b32 s76, m0
	s_mov_b32 m0, s75
	s_nop 0
	global_load_lds_dwordx4 v[80:81], off
	s_mov_b32 m0, s76
	v_lshl_add_u64 v[80:81], v[200:201], 0, s[22:23]
	s_addk_i32 s1, 0x4400
	s_mov_b32 s75, m0
	s_mov_b32 m0, s1
	s_nop 0
	global_load_lds_dwordx4 v[80:81], off
	s_mov_b32 m0, s75
	ds_read_b128 v[80:83], v231 offset:49152
	ds_read_b128 v[156:159], v231 offset:57344
	ds_read_b128 v[240:243], v232 offset:49152
	ds_read_b128 v[152:155], v232 offset:57344
	ds_read_b128 v[244:247], v233 offset:49152
	ds_read_b128 v[148:151], v233 offset:57344
	ds_read_b128 v[248:251], v234 offset:49152
	ds_read_b128 v[144:147], v234 offset:57344
	s_waitcnt lgkmcnt(7)
	v_mfma_f32_32x32x16_bf16 v[80:95], v[80:83], v[116:119], 0
	s_waitcnt lgkmcnt(5)
	v_mfma_f32_32x32x16_bf16 v[80:95], v[240:243], v[112:115], v[80:95]
	ds_read_b128 v[240:243], v235 offset:49152
	ds_read_b128 v[140:143], v235 offset:57344
	v_exp_f32_e32 v217, v64
	v_exp_f32_e32 v215, v65
	s_waitcnt lgkmcnt(5)
	v_mfma_f32_32x32x16_bf16 v[80:95], v[244:247], v[108:111], v[80:95]
	ds_read_b128 v[244:247], v236 offset:49152
	ds_read_b128 v[136:139], v236 offset:57344
	v_exp_f32_e32 v216, v66
	v_exp_f32_e32 v214, v67
	s_waitcnt lgkmcnt(5)
	v_mfma_f32_32x32x16_bf16 v[80:95], v[248:251], v[104:107], v[80:95]
	ds_read_b128 v[248:251], v237 offset:49152
	ds_read_b128 v[124:127], v229
	ds_read_b128 v[132:135], v237 offset:57344
	v_exp_f32_e32 v213, v68
	v_exp_f32_e32 v211, v69
	s_waitcnt lgkmcnt(6)
	v_mfma_f32_32x32x16_bf16 v[80:95], v[240:243], v[100:103], v[80:95]
	ds_read_b128 v[240:243], v238 offset:49152
	ds_read_b128 v[120:123], v229 offset:1024
	ds_read_b128 v[128:131], v238 offset:57344
	v_exp_f32_e32 v212, v70
	v_exp_f32_e32 v210, v71
	s_waitcnt lgkmcnt(7)
	v_mfma_f32_32x32x16_bf16 v[80:95], v[244:247], v[96:99], v[80:95]
	v_exp_f32_e32 v209, v72
	v_exp_f32_e32 v207, v73
	v_exp_f32_e32 v208, v74
	s_waitcnt lgkmcnt(4)
	v_mfma_f32_32x32x16_bf16 v[80:95], v[248:251], v[124:127], v[80:95]
	v_exp_f32_e32 v206, v75
	v_exp_f32_e32 v205, v76
	v_exp_f32_e32 v203, v77
	s_waitcnt lgkmcnt(1)
	v_mfma_f32_32x32x16_bf16 v[80:95], v[240:243], v[120:123], v[80:95]
	v_exp_f32_e32 v204, v78
	v_exp_f32_e32 v202, v79
	ds_read_b64_tr_b16 v[184:185], v228 offset:0
	ds_read_b64_tr_b16 v[186:187], v228 offset:0x800
	ds_read_b64_tr_b16 v[188:189], v228 offset:0x1000
	ds_read_b64_tr_b16 v[190:191], v228 offset:0x1800
	ds_read_b64_tr_b16 v[192:193], v228 offset:0x2000
	ds_read_b64_tr_b16 v[194:195], v228 offset:0x2800
	ds_read_b64_tr_b16 v[196:197], v228 offset:0x3000
	ds_read_b64_tr_b16 v[198:199], v228 offset:0x3800
	v_cvt_pk_bf16_f32 v64, v183, v181
	v_cvt_pk_bf16_f32 v65, v182, v180
	v_cvt_pk_bf16_f32 v66, v179, v177
	v_cvt_pk_bf16_f32 v67, v178, v176
	v_cvt_pk_bf16_f32 v68, v175, v173
	v_cvt_pk_bf16_f32 v69, v174, v172
	v_cvt_pk_bf16_f32 v70, v171, v169
	v_cvt_pk_bf16_f32 v71, v170, v168
	v_cvt_pk_bf16_f32 v72, v217, v215
	v_cvt_pk_bf16_f32 v73, v216, v214
	v_cvt_pk_bf16_f32 v74, v213, v211
	v_cvt_pk_bf16_f32 v75, v212, v210
	v_cvt_pk_bf16_f32 v76, v209, v207
	v_cvt_pk_bf16_f32 v77, v208, v206
	v_cvt_pk_bf16_f32 v78, v205, v203
	v_cvt_pk_bf16_f32 v79, v204, v202
	s_nop 0
	v_permlane32_swap_b32_e32 v64, v66
	v_permlane32_swap_b32_e32 v65, v67
	v_permlane32_swap_b32_e32 v68, v70
	v_permlane32_swap_b32_e32 v69, v71
	v_permlane32_swap_b32_e32 v72, v74
	v_permlane32_swap_b32_e32 v73, v75
	v_permlane32_swap_b32_e32 v76, v78
	v_permlane32_swap_b32_e32 v77, v79
	s_waitcnt lgkmcnt(0)
	s_nop 0
	v_mfma_f32_32x32x16_bf16 v[0:15], v[64:67], v[184:187], v[0:15]
	ds_read_b64_tr_b16 v[184:185], v228 offset:0x200
	ds_read_b64_tr_b16 v[186:187], v228 offset:0xa00
	v_mfma_f32_32x32x16_bf16 v[0:15], v[68:71], v[188:191], v[0:15]
	ds_read_b64_tr_b16 v[188:189], v228 offset:0x1200
	ds_read_b64_tr_b16 v[190:191], v228 offset:0x1a00
	v_mfma_f32_32x32x16_bf16 v[0:15], v[72:75], v[192:195], v[0:15]
	ds_read_b64_tr_b16 v[192:193], v228 offset:0x2200
	ds_read_b64_tr_b16 v[194:195], v228 offset:0x2a00
	ds_read_b64_tr_b16 v[240:241], v228 offset:0x3200
	ds_read_b64_tr_b16 v[242:243], v228 offset:0x3a00
	s_waitcnt lgkmcnt(0)
	v_mfma_f32_32x32x16_bf16 v[0:15], v[76:79], v[196:199], v[0:15]
	v_mfma_f32_32x32x16_bf16 v[16:31], v[64:67], v[184:187], v[16:31]
	ds_read_b64_tr_b16 v[184:185], v228 offset:0x400
	ds_read_b64_tr_b16 v[186:187], v228 offset:0xc00
	v_mfma_f32_32x32x16_bf16 v[16:31], v[68:71], v[188:191], v[16:31]
	ds_read_b64_tr_b16 v[188:189], v228 offset:0x1400
	ds_read_b64_tr_b16 v[190:191], v228 offset:0x1c00
	v_mfma_f32_32x32x16_bf16 v[16:31], v[72:75], v[192:195], v[16:31]
	ds_read_b64_tr_b16 v[192:193], v228 offset:0x2400
	ds_read_b64_tr_b16 v[194:195], v228 offset:0x2c00
	ds_read_b64_tr_b16 v[196:197], v228 offset:0x3400
	ds_read_b64_tr_b16 v[198:199], v228 offset:0x3c00
	s_waitcnt lgkmcnt(0)
	v_mfma_f32_32x32x16_bf16 v[16:31], v[76:79], v[240:243], v[16:31]
	v_mfma_f32_32x32x16_bf16 v[32:47], v[64:67], v[184:187], v[32:47]
	ds_read_b64_tr_b16 v[184:185], v228 offset:0x600
	ds_read_b64_tr_b16 v[186:187], v228 offset:0xe00
	v_mfma_f32_32x32x16_bf16 v[32:47], v[68:71], v[188:191], v[32:47]
	ds_read_b64_tr_b16 v[188:189], v228 offset:0x1600
	ds_read_b64_tr_b16 v[190:191], v228 offset:0x1e00
	v_mfma_f32_32x32x16_bf16 v[32:47], v[72:75], v[192:195], v[32:47]
	ds_read_b64_tr_b16 v[192:193], v228 offset:0x2600
	ds_read_b64_tr_b16 v[194:195], v228 offset:0x2e00
	ds_read_b64_tr_b16 v[240:241], v228 offset:0x3600
	ds_read_b64_tr_b16 v[242:243], v228 offset:0x3e00
	s_waitcnt lgkmcnt(0)
	v_mfma_f32_32x32x16_bf16 v[32:47], v[76:79], v[196:199], v[32:47]
	s_cmp_ge_u32 s100, 0x100
	s_cbranch_scc1 .Latt_a_late_half
; #define SBAR() __builtin_amdgcn_sched_barrier(0)
; #define DMA_K(t, buf) do { const char* kb_ = (const char*)Kh + (size_t)(t) * TILEB; \
;         glds16(kb_ + ksrc[0], (unsigned)__builtin_amdgcn_readfirstlane(lds0 + OFF_K + (buf) * SHM_K + (DQK == 128 ? widu * 2048 : widu * 1024))); \
;         if (DQK == 128) glds16(kb_ + ksrc[1], (unsigned)__builtin_amdgcn_readfirstlane(lds0 + OFF_K + (buf) * SHM_K + widu * 2048 + 1024)); } while (0)
; #define DMA_V(t, buf) do { const char* vb_ = (const char*)Vh + (size_t)(t) * TILEB; \
;         glds16(vb_ + vsrc[0], (unsigned)__builtin_amdgcn_readfirstlane(lds0 + (buf) * SHM_V + widu * 2048)); \
;         glds16(vb_ + vsrc[1], (unsigned)__builtin_amdgcn_readfirstlane(lds0 + (buf) * SHM_V + widu * 2048 + 1024)); } while (0)
; #define WBAR0() do { asm volatile("s_waitcnt vmcnt(0)" ::: "memory"); __syncthreads(); } while (0)
; #define EXPH(P) do { _Pragma("unroll") for (int r = 0; r < 16; ++r) P[r] = __builtin_amdgcn_exp2f(P[r]); } while (0)
;     ...
;         pv_d0(o, vb0, pa0, pa1, pa2, pa3);
;         if (!isY) { EXPH(pB0); }
;         WBAR0();
;         DMA_K(k + 2, 1); DMA_V(k + 1, 0); SBAR();
;         if (isY) { EXPH(pB0); }
;         SBAR(); qkt_mix<DQK, NREG>(pA0, pA1, K_lds, qr, qs, r32, hi);
	v_mfma_f32_32x32x16_bf16 v[48:63], v[64:67], v[184:187], v[48:63]
	v_exp_f32_e32 v199, v80
	v_exp_f32_e32 v197, v81
	v_exp_f32_e32 v198, v82
	v_exp_f32_e32 v196, v83
	v_pk_add_f32 v[80:81], v[182:183], v[216:217]
	v_pk_add_f32 v[82:83], v[180:181], v[214:215]
	v_pk_add_f32 v[80:81], v[80:81], 0 op_sel_hi:[1,0]
	v_mfma_f32_32x32x16_bf16 v[48:63], v[68:71], v[188:191], v[48:63]
	v_add_f32_e64 v82, v82, 0
	v_add_f32_e64 v83, v83, 0
	v_exp_f32_e32 v191, v88
	v_exp_f32_e32 v189, v89
	v_exp_f32_e32 v190, v90
	v_exp_f32_e32 v188, v91
	v_pk_add_f32 v[88:89], v[174:175], v[208:209]
	v_pk_add_f32 v[90:91], v[172:173], v[206:207]
	v_mfma_f32_32x32x16_bf16 v[48:63], v[72:75], v[192:195], v[48:63]
	v_exp_f32_e32 v195, v84
	v_exp_f32_e32 v193, v85
	v_exp_f32_e32 v194, v86
	v_exp_f32_e32 v192, v87
	v_pk_add_f32 v[84:85], v[178:179], v[212:213]
	v_pk_add_f32 v[86:87], v[176:177], v[210:211]
	v_pk_add_f32 v[80:81], v[84:85], v[80:81]
	v_mfma_f32_32x32x16_bf16 v[48:63], v[76:79], v[240:243], v[48:63]
	v_add_f32_e64 v82, v86, v82
	v_add_f32_e64 v83, v87, v83
	v_exp_f32_e32 v187, v92
	v_exp_f32_e32 v185, v93
	v_exp_f32_e32 v186, v94
	v_exp_f32_e32 v184, v95
	v_pk_add_f32 v[92:93], v[170:171], v[204:205]
	v_pk_add_f32 v[94:95], v[168:169], v[202:203]
	v_mfma_f32_32x32x16_bf16 v[64:79], v[156:159], v[116:119], 0
	v_add_f32_e64 v80, v88, v80
	v_add_f32_e64 v81, v89, v81
	v_add_f32_e64 v82, v90, v82
	v_add_f32_e64 v83, v91, v83
	v_add_f32_e64 v80, v92, v80
	v_add_f32_e64 v81, v93, v81
	v_pk_add_f32 v[82:83], v[94:95], v[82:83]
	s_waitcnt vmcnt(0)
	s_waitcnt lgkmcnt(0)
	v_pk_add_f32 v[80:81], v[82:83], v[80:81]
	v_mfma_f32_32x32x16_bf16 v[64:79], v[152:155], v[112:115], v[64:79]
	v_add_f32_e32 v216, v80, v81
	s_barrier
	v_lshl_add_u64 v[80:81], s[44:45], 0, v[160:161]
	s_mov_b32 s1, m0
	s_mov_b32 m0, s73
	s_nop 0
	global_load_lds_dwordx4 v[80:81], off
	s_mov_b32 m0, s1
	v_lshl_add_u64 v[80:81], s[44:45], 0, v[162:163]
	s_mov_b32 s1, m0
	s_mov_b32 m0, s74
	s_nop 0
	global_load_lds_dwordx4 v[80:81], off
	s_mov_b32 m0, s1
	v_mfma_f32_32x32x16_bf16 v[64:79], v[148:151], v[108:111], v[64:79]
	v_lshl_add_u64 v[80:81], v[200:201], 0, s[26:27]
	s_mov_b32 s1, m0
	s_mov_b32 m0, s72
	s_nop 0
	global_load_lds_dwordx4 v[80:81], off
	s_mov_b32 m0, s1
	v_lshl_add_u64 v[80:81], v[200:201], 0, s[28:29]
	s_mov_b32 s1, m0
	s_mov_b32 m0, s0
	s_nop 0
	global_load_lds_dwordx4 v[80:81], off
	s_mov_b32 m0, s1
	v_mfma_f32_32x32x16_bf16 v[64:79], v[144:147], v[104:107], v[64:79]
	v_mfma_f32_32x32x16_bf16 v[64:79], v[140:143], v[100:103], v[64:79]
	v_mfma_f32_32x32x16_bf16 v[64:79], v[136:139], v[96:99], v[64:79]
	v_mfma_f32_32x32x16_bf16 v[64:79], v[132:135], v[124:127], v[64:79]
	v_mfma_f32_32x32x16_bf16 v[64:79], v[128:131], v[120:123], v[64:79]
	s_branch .Latt_a_join_half
.Latt_a_late_half:
	v_mfma_f32_32x32x16_bf16 v[48:63], v[64:67], v[184:187], v[48:63]
	v_mfma_f32_32x32x16_bf16 v[48:63], v[68:71], v[188:191], v[48:63]
	v_mfma_f32_32x32x16_bf16 v[48:63], v[72:75], v[192:195], v[48:63]
	v_mfma_f32_32x32x16_bf16 v[48:63], v[76:79], v[240:243], v[48:63]
	v_mfma_f32_32x32x16_bf16 v[64:79], v[156:159], v[116:119], 0
	s_waitcnt vmcnt(0)
	s_waitcnt lgkmcnt(0)
	v_mfma_f32_32x32x16_bf16 v[64:79], v[152:155], v[112:115], v[64:79]
	s_barrier
	v_lshl_add_u64 v[240:241], s[44:45], 0, v[160:161]
	s_mov_b32 s1, m0
	s_mov_b32 m0, s73
	s_nop 0
	global_load_lds_dwordx4 v[240:241], off
	s_mov_b32 m0, s1
	v_lshl_add_u64 v[240:241], s[44:45], 0, v[162:163]
	s_mov_b32 s1, m0
	s_mov_b32 m0, s74
	s_nop 0
	global_load_lds_dwordx4 v[240:241], off
	s_mov_b32 m0, s1
	v_mfma_f32_32x32x16_bf16 v[64:79], v[148:151], v[108:111], v[64:79]
	v_exp_f32_e32 v199, v80
	v_exp_f32_e32 v197, v81
	v_exp_f32_e32 v198, v82
	v_exp_f32_e32 v196, v83
	v_pk_add_f32 v[80:81], v[182:183], v[216:217]
	v_pk_add_f32 v[82:83], v[180:181], v[214:215]
	v_pk_add_f32 v[80:81], v[80:81], 0 op_sel_hi:[1,0]
	v_add_f32_e64 v82, v82, 0
	v_add_f32_e64 v83, v83, 0
	v_lshl_add_u64 v[240:241], v[200:201], 0, s[26:27]
	s_mov_b32 s1, m0
	s_mov_b32 m0, s72
	s_nop 0
	global_load_lds_dwordx4 v[240:241], off
	s_mov_b32 m0, s1
	v_lshl_add_u64 v[240:241], v[200:201], 0, s[28:29]
	s_mov_b32 s1, m0
	s_mov_b32 m0, s0
	s_nop 0
	global_load_lds_dwordx4 v[240:241], off
	s_mov_b32 m0, s1
	v_mfma_f32_32x32x16_bf16 v[64:79], v[144:147], v[104:107], v[64:79]
	v_exp_f32_e32 v191, v88
	v_exp_f32_e32 v189, v89
	v_exp_f32_e32 v190, v90
	v_exp_f32_e32 v188, v91
	v_pk_add_f32 v[88:89], v[174:175], v[208:209]
	v_pk_add_f32 v[90:91], v[172:173], v[206:207]
	v_exp_f32_e32 v195, v84
	v_exp_f32_e32 v193, v85
	v_mfma_f32_32x32x16_bf16 v[64:79], v[140:143], v[100:103], v[64:79]
	v_exp_f32_e32 v194, v86
	v_exp_f32_e32 v192, v87
	v_pk_add_f32 v[84:85], v[178:179], v[212:213]
	v_pk_add_f32 v[86:87], v[176:177], v[210:211]
	v_pk_add_f32 v[80:81], v[84:85], v[80:81]
	v_add_f32_e64 v82, v86, v82
	v_add_f32_e64 v83, v87, v83
	v_exp_f32_e32 v187, v92
	v_mfma_f32_32x32x16_bf16 v[64:79], v[136:139], v[96:99], v[64:79]
	v_exp_f32_e32 v185, v93
	v_exp_f32_e32 v186, v94
	v_exp_f32_e32 v184, v95
	v_pk_add_f32 v[92:93], v[170:171], v[204:205]
	v_pk_add_f32 v[94:95], v[168:169], v[202:203]
	v_add_f32_e64 v80, v88, v80
	v_add_f32_e64 v81, v89, v81
	v_add_f32_e64 v82, v90, v82
	v_mfma_f32_32x32x16_bf16 v[64:79], v[132:135], v[124:127], v[64:79]
	v_add_f32_e64 v83, v91, v83
	v_add_f32_e64 v80, v92, v80
	v_add_f32_e64 v81, v93, v81
	v_pk_add_f32 v[82:83], v[94:95], v[82:83]
	s_nop 0
	v_pk_add_f32 v[80:81], v[82:83], v[80:81]
	s_nop 0
	v_add_f32_e32 v216, v80, v81
	v_mfma_f32_32x32x16_bf16 v[64:79], v[128:131], v[120:123], v[64:79]
	s_branch .Latt_a_join_half
; #define SBAR() __builtin_amdgcn_sched_barrier(0)
; template <int D0> __device__ __forceinline__ void pv_one(f32x16& od, int vb, bf16x8 pa0, bf16x8 pa1, bf16x8 pa2, bf16x8 pa3) {
;     const s16x4 l0 = tr_read<v_rd_off(D0, 0, 0)>(vb), h0 = tr_read<v_rd_off(D0, 0, 1)>(vb), l1 = tr_read<v_rd_off(D0, 1, 0)>(vb), h1 = tr_read<v_rd_off(D0, 1, 1)>(vb);
;     const s16x4 l2 = tr_read<v_rd_off(D0, 2, 0)>(vb), h2 = tr_read<v_rd_off(D0, 2, 1)>(vb), l3 = tr_read<v_rd_off(D0, 3, 0)>(vb), h3 = tr_read<v_rd_off(D0, 3, 1)>(vb);
;     asm volatile("s_waitcnt lgkmcnt(0)" ::: "memory"); SBAR();
;     ...
;     od = __builtin_amdgcn_mfma_f32_32x32x16_bf16(pa0, PK(l0, h0), od, 0, 0, 0);
;     od = __builtin_amdgcn_mfma_f32_32x32x16_bf16(pa1, PK(l1, h1), od, 0, 0, 0);
;     od = __builtin_amdgcn_mfma_f32_32x32x16_bf16(pa2, PK(l2, h2), od, 0, 0, 0);
;     od = __builtin_amdgcn_mfma_f32_32x32x16_bf16(pa3, PK(l3, h3), od, 0, 0, 0);
;     ...
; }
; __device__ __forceinline__ void pv_d0(f32x16* o, int vb, bf16x8 pa0, bf16x8 pa1, bf16x8 pa2, bf16x8 pa3) {
;     pv_one<0>(o[0], vb, pa0, pa1, pa2, pa3); pv_one<1>(o[1], vb, pa0, pa1, pa2, pa3); pv_one<2>(o[2], vb, pa0, pa1, pa2, pa3); pv_one<3>(o[3], vb, pa0, pa1, pa2, pa3);
;     ...
;         SBAR(); qkt_mix<DQK, NREG>(pA0, pA1, K_lds, qr, qs, r32, hi);
;         finishSM<true>(pB0, pB1, dummy_a, l_reg, pa0, pa1, pa2, pa3); SBAR();
;         pv_d0(o, vb0 + SHM_V, pa0, pa1, pa2, pa3);
.Latt_a_join_half:
	ds_read_b128 v[80:83], v231 offset:32768
	ds_read_b128 v[148:151], v231 offset:40960
	ds_read_b128 v[240:243], v232 offset:32768
	ds_read_b128 v[152:155], v232 offset:40960
	ds_read_b128 v[244:247], v233 offset:32768
	ds_read_b128 v[156:159], v233 offset:40960
	ds_read_b128 v[248:251], v234 offset:32768
	ds_read_b128 v[144:147], v234 offset:40960
	s_waitcnt lgkmcnt(7)
	v_mfma_f32_32x32x16_bf16 v[80:95], v[80:83], v[116:119], 0
	s_waitcnt lgkmcnt(5)
	v_mfma_f32_32x32x16_bf16 v[80:95], v[240:243], v[112:115], v[80:95]
	ds_read_b128 v[240:243], v235 offset:32768
	ds_read_b128 v[140:143], v235 offset:40960
	s_waitcnt lgkmcnt(5)
	v_mfma_f32_32x32x16_bf16 v[80:95], v[244:247], v[108:111], v[80:95]
	ds_read_b128 v[244:247], v236 offset:32768
	ds_read_b128 v[136:139], v236 offset:40960
	v_exp_f32_e32 v215, v64
	v_exp_f32_e32 v213, v65
	s_waitcnt lgkmcnt(5)
	v_mfma_f32_32x32x16_bf16 v[80:95], v[248:251], v[104:107], v[80:95]
	ds_read_b128 v[248:251], v237 offset:32768
	ds_read_b128 v[124:127], v229
	ds_read_b128 v[128:131], v237 offset:40960
	v_exp_f32_e32 v214, v66
	v_exp_f32_e32 v212, v67
	s_waitcnt lgkmcnt(6)
	v_mfma_f32_32x32x16_bf16 v[80:95], v[240:243], v[100:103], v[80:95]
	ds_read_b128 v[240:243], v238 offset:32768
	ds_read_b128 v[120:123], v229 offset:1024
	ds_read_b128 v[132:135], v238 offset:40960
	v_exp_f32_e32 v211, v68
	v_exp_f32_e32 v209, v69
	v_exp_f32_e32 v210, v70
	s_waitcnt lgkmcnt(7)
	v_mfma_f32_32x32x16_bf16 v[80:95], v[244:247], v[96:99], v[80:95]
	v_exp_f32_e32 v208, v71
	v_exp_f32_e32 v207, v72
	v_exp_f32_e32 v205, v73
	s_waitcnt lgkmcnt(4)
	v_mfma_f32_32x32x16_bf16 v[80:95], v[248:251], v[124:127], v[80:95]
	v_exp_f32_e32 v206, v74
	v_exp_f32_e32 v204, v75
	v_exp_f32_e32 v203, v76
	s_waitcnt lgkmcnt(1)
	v_mfma_f32_32x32x16_bf16 v[80:95], v[240:243], v[120:123], v[80:95]
	v_exp_f32_e32 v201, v77
	v_exp_f32_e32 v202, v78
	v_exp_f32_e32 v200, v79
	ds_read_b64_tr_b16 v[68:69], v227 offset:0
	ds_read_b64_tr_b16 v[70:71], v227 offset:0x800
	ds_read_b64_tr_b16 v[72:73], v227 offset:0x1000
	ds_read_b64_tr_b16 v[74:75], v227 offset:0x1800
	ds_read_b64_tr_b16 v[76:77], v227 offset:0x2000
	ds_read_b64_tr_b16 v[78:79], v227 offset:0x2800
	ds_read_b64_tr_b16 v[180:181], v227 offset:0x3000
	ds_read_b64_tr_b16 v[182:183], v227 offset:0x3800
	v_cvt_pk_bf16_f32 v64, v199, v197
	v_cvt_pk_bf16_f32 v65, v198, v196
	v_cvt_pk_bf16_f32 v66, v195, v193
	v_cvt_pk_bf16_f32 v67, v194, v192
	v_cvt_pk_bf16_f32 v168, v191, v189
	v_cvt_pk_bf16_f32 v169, v190, v188
	v_cvt_pk_bf16_f32 v170, v187, v185
	v_cvt_pk_bf16_f32 v171, v186, v184
	v_cvt_pk_bf16_f32 v172, v215, v213
	v_cvt_pk_bf16_f32 v173, v214, v212
	v_cvt_pk_bf16_f32 v174, v211, v209
	v_cvt_pk_bf16_f32 v175, v210, v208
	v_cvt_pk_bf16_f32 v176, v207, v205
	v_cvt_pk_bf16_f32 v177, v206, v204
	v_cvt_pk_bf16_f32 v178, v203, v201
	v_cvt_pk_bf16_f32 v179, v202, v200
	s_nop 0
	v_permlane32_swap_b32_e32 v64, v66
	v_permlane32_swap_b32_e32 v65, v67
	v_permlane32_swap_b32_e32 v168, v170
	v_permlane32_swap_b32_e32 v169, v171
	v_permlane32_swap_b32_e32 v172, v174
	v_permlane32_swap_b32_e32 v173, v175
	v_permlane32_swap_b32_e32 v176, v178
	v_permlane32_swap_b32_e32 v177, v179
	s_waitcnt lgkmcnt(0)
	s_nop 0
	v_mfma_f32_32x32x16_bf16 v[0:15], v[64:67], v[68:71], v[0:15]
	ds_read_b64_tr_b16 v[68:69], v227 offset:0x200
	ds_read_b64_tr_b16 v[70:71], v227 offset:0xa00
	v_mfma_f32_32x32x16_bf16 v[0:15], v[168:171], v[72:75], v[0:15]
	ds_read_b64_tr_b16 v[72:73], v227 offset:0x1200
	ds_read_b64_tr_b16 v[74:75], v227 offset:0x1a00
	v_mfma_f32_32x32x16_bf16 v[0:15], v[172:175], v[76:79], v[0:15]
	ds_read_b64_tr_b16 v[76:77], v227 offset:0x2200
	ds_read_b64_tr_b16 v[78:79], v227 offset:0x2a00
	ds_read_b64_tr_b16 v[240:241], v227 offset:0x3200
	ds_read_b64_tr_b16 v[242:243], v227 offset:0x3a00
	s_waitcnt lgkmcnt(0)
	v_mfma_f32_32x32x16_bf16 v[0:15], v[176:179], v[180:183], v[0:15]
	v_mfma_f32_32x32x16_bf16 v[16:31], v[64:67], v[68:71], v[16:31]
	ds_read_b64_tr_b16 v[68:69], v227 offset:0x400
	ds_read_b64_tr_b16 v[70:71], v227 offset:0xc00
	v_mfma_f32_32x32x16_bf16 v[16:31], v[168:171], v[72:75], v[16:31]
	ds_read_b64_tr_b16 v[72:73], v227 offset:0x1400
	ds_read_b64_tr_b16 v[74:75], v227 offset:0x1c00
	v_mfma_f32_32x32x16_bf16 v[16:31], v[172:175], v[76:79], v[16:31]
	ds_read_b64_tr_b16 v[76:77], v227 offset:0x2400
	ds_read_b64_tr_b16 v[78:79], v227 offset:0x2c00
	ds_read_b64_tr_b16 v[180:181], v227 offset:0x3400
	ds_read_b64_tr_b16 v[182:183], v227 offset:0x3c00
	s_waitcnt lgkmcnt(0)
	v_mfma_f32_32x32x16_bf16 v[16:31], v[176:179], v[240:243], v[16:31]
	v_mfma_f32_32x32x16_bf16 v[32:47], v[64:67], v[68:71], v[32:47]
	ds_read_b64_tr_b16 v[68:69], v227 offset:0x600
	ds_read_b64_tr_b16 v[70:71], v227 offset:0xe00
	ds_read_b64_tr_b16 v[240:241], v227 offset:0x1600
	ds_read_b64_tr_b16 v[242:243], v227 offset:0x1e00
	ds_read_b64_tr_b16 v[244:245], v227 offset:0x2600
	ds_read_b64_tr_b16 v[246:247], v227 offset:0x2e00
	ds_read_b64_tr_b16 v[248:249], v227 offset:0x3600
	v_mfma_f32_32x32x16_bf16 v[32:47], v[168:171], v[72:75], v[32:47]
	ds_read_b64_tr_b16 v[250:251], v227 offset:0x3e00
	s_waitcnt lgkmcnt(0)
	v_mfma_f32_32x32x16_bf16 v[32:47], v[172:175], v[76:79], v[32:47]
	v_mfma_f32_32x32x16_bf16 v[32:47], v[176:179], v[180:183], v[32:47]
	v_mfma_f32_32x32x16_bf16 v[48:63], v[64:67], v[68:71], v[48:63]
	v_exp_f32_e32 v183, v80
	v_exp_f32_e32 v181, v81
	v_exp_f32_e32 v182, v82
	v_exp_f32_e32 v180, v83
	v_pk_add_f32 v[80:81], v[198:199], v[214:215]
	v_pk_add_f32 v[82:83], v[196:197], v[212:213]
	v_pk_add_f32 v[80:81], v[80:81], 0 op_sel_hi:[1,0]
	v_mfma_f32_32x32x16_bf16 v[64:79], v[148:151], v[116:119], 0
	v_add_f32_e64 v82, v82, 0
	v_add_f32_e64 v83, v83, 0
	s_add_i32 s55, s55, 2
	s_waitcnt vmcnt(0)
	s_add_u32 s44, s44, 0xc0000
	s_addc_u32 s45, s45, 0
	s_cmp_gt_u32 s55, 64
	s_waitcnt lgkmcnt(0)
	v_mfma_f32_32x32x16_bf16 v[64:79], v[152:155], v[112:115], v[64:79]
	s_barrier
; #define SBAR() __builtin_amdgcn_sched_barrier(0)
; #define DMA_V(t, buf) do { const char* vb_ = (const char*)Vh + (size_t)(t) * TILEB; \
;         glds16(vb_ + vsrc[0], (unsigned)__builtin_amdgcn_readfirstlane(lds0 + (buf) * SHM_V + widu * 2048)); \
;         glds16(vb_ + vsrc[1], (unsigned)__builtin_amdgcn_readfirstlane(lds0 + (buf) * SHM_V + widu * 2048 + 1024)); } while (0)
; #define WBAR0() do { asm volatile("s_waitcnt vmcnt(0)" ::: "memory"); __syncthreads(); } while (0)
; #define EXPH(P) do { _Pragma("unroll") for (int r = 0; r < 16; ++r) P[r] = __builtin_amdgcn_exp2f(P[r]); } while (0)
;     ...
;         pv_d0(o, vb0 + SHM_V, pa0, pa1, pa2, pa3);
;         if (!isY) { EXPH(pA0); }
;         WBAR0();
;     }
;     DMA_V(NT - 1, 1); SBAR();
;     if (isY) { EXPH(pA0); }
;     SBAR(); qkt_mix<DQK, NREG>(pB0, pB1, K_lds + SHM_K, qr, qs, r32, hi);
	v_mfma_f32_32x32x16_bf16 v[64:79], v[156:159], v[108:111], v[64:79]
	v_mfma_f32_32x32x16_bf16 v[64:79], v[144:147], v[104:107], v[64:79]
	v_mfma_f32_32x32x16_bf16 v[64:79], v[140:143], v[100:103], v[64:79]
	v_add_f32_e32 v140, v230, v216
	v_mfma_f32_32x32x16_bf16 v[48:63], v[168:171], v[240:243], v[48:63]
	v_exp_f32_e32 v171, v92
	v_exp_f32_e32 v169, v93
	v_exp_f32_e32 v170, v94
	v_exp_f32_e32 v168, v95
	v_pk_add_f32 v[92:93], v[186:187], v[202:203]
	v_pk_add_f32 v[94:95], v[184:185], v[200:201]
	v_mfma_f32_32x32x16_bf16 v[64:79], v[136:139], v[96:99], v[64:79]
	v_mfma_f32_32x32x16_bf16 v[48:63], v[172:175], v[244:247], v[48:63]
	v_exp_f32_e32 v175, v88
	v_exp_f32_e32 v173, v89
	v_exp_f32_e32 v174, v90
	v_exp_f32_e32 v172, v91
	v_pk_add_f32 v[88:89], v[190:191], v[206:207]
	v_pk_add_f32 v[90:91], v[188:189], v[204:205]
	v_mfma_f32_32x32x16_bf16 v[64:79], v[128:131], v[124:127], v[64:79]
	v_mfma_f32_32x32x16_bf16 v[48:63], v[176:179], v[248:251], v[48:63]
	v_exp_f32_e32 v179, v84
	v_exp_f32_e32 v177, v85
	v_exp_f32_e32 v178, v86
	v_exp_f32_e32 v176, v87
	v_pk_add_f32 v[84:85], v[194:195], v[210:211]
	v_pk_add_f32 v[86:87], v[192:193], v[208:209]
	v_pk_add_f32 v[80:81], v[84:85], v[80:81]
	v_mfma_f32_32x32x16_bf16 v[64:79], v[132:135], v[120:123], v[64:79]
	v_add_f32_e64 v82, v86, v82
	v_add_f32_e64 v83, v87, v83
	v_add_f32_e64 v80, v88, v80
	v_add_f32_e64 v81, v89, v81
	v_add_f32_e64 v82, v90, v82
	v_add_f32_e64 v83, v91, v83
	v_pk_add_f32 v[80:81], v[92:93], v[80:81]
	v_pk_add_f32 v[82:83], v[94:95], v[82:83]
	s_nop 0
	v_pk_add_f32 v[80:81], v[82:83], v[80:81]
	s_nop 0
	v_add_f32_e32 v80, v80, v81
	v_add_f32_e32 v230, v140, v80
	s_cbranch_scc0 .LBB0_529
	s_cmp_lg_u32 0, -1
	s_cselect_b32 s0, 0, 0
	s_add_i32 s0, s0, s52
	v_lshl_add_u64 v[80:81], v[166:167], 0, s[38:39]
	s_add_i32 s1, s0, 0x4000
	s_mov_b32 s44, m0
	s_mov_b32 m0, s1
	s_nop 0
	global_load_lds_dwordx4 v[80:81], off
	s_mov_b32 m0, s44
	v_lshl_add_u64 v[80:81], v[166:167], 0, s[40:41]
	s_addk_i32 s0, 0x4400
	s_mov_b32 s1, m0
	s_mov_b32 m0, s0
	s_nop 0
	global_load_lds_dwordx4 v[80:81], off
	s_mov_b32 m0, s1
	ds_read_b128 v[80:83], v231 offset:49152
	ds_read_b128 v[144:147], v231 offset:57344
	ds_read_b128 v[120:123], v232 offset:49152
	ds_read_b128 v[148:151], v232 offset:57344
	s_waitcnt lgkmcnt(3)
	v_mfma_f32_32x32x16_bf16 v[80:95], v[80:83], v[116:119], 0
	s_waitcnt lgkmcnt(1)
	v_mfma_f32_32x32x16_bf16 v[80:95], v[120:123], v[112:115], v[80:95]
	ds_read_b128 v[120:123], v233 offset:49152
	ds_read_b128 v[152:155], v233 offset:57344
	s_waitcnt lgkmcnt(1)
	v_mfma_f32_32x32x16_bf16 v[80:95], v[120:123], v[108:111], v[80:95]
	ds_read_b128 v[120:123], v234 offset:49152
	ds_read_b128 v[156:159], v234 offset:57344
	s_waitcnt lgkmcnt(1)
	v_mfma_f32_32x32x16_bf16 v[80:95], v[120:123], v[104:107], v[80:95]
	ds_read_b128 v[120:123], v235 offset:49152
	ds_read_b128 v[140:143], v235 offset:57344
	s_waitcnt lgkmcnt(1)
	v_mfma_f32_32x32x16_bf16 v[80:95], v[120:123], v[100:103], v[80:95]
	ds_read_b128 v[120:123], v236 offset:49152
	ds_read_b128 v[136:139], v236 offset:57344
	s_waitcnt lgkmcnt(1)
	v_mfma_f32_32x32x16_bf16 v[80:95], v[120:123], v[96:99], v[80:95]
	ds_read_b128 v[128:131], v237 offset:49152
	ds_read_b128 v[124:127], v229
	ds_read_b128 v[132:135], v237 offset:57344
	ds_read_b128 v[120:123], v229 offset:1024
	s_waitcnt lgkmcnt(2)
	v_mfma_f32_32x32x16_bf16 v[80:95], v[128:131], v[124:127], v[80:95]
	ds_read_b128 v[162:165], v238 offset:49152
	ds_read_b128 v[128:131], v238 offset:57344
	s_waitcnt lgkmcnt(1)
	v_mfma_f32_32x32x16_bf16 v[80:95], v[162:165], v[120:123], v[80:95]
	v_exp_f32_e32 v163, v66
	v_exp_f32_e32 v164, v67
	v_exp_f32_e32 v167, v70
	v_exp_f32_e32 v184, v71
	v_exp_f32_e32 v187, v74
	v_exp_f32_e32 v160, v64
	v_exp_f32_e32 v188, v75
	v_add_f32_e32 v64, v182, v163
	v_exp_f32_e32 v162, v65
	v_exp_f32_e32 v191, v78
	v_add_f32_e32 v64, 0, v64
	v_add_f32_e32 v65, v180, v164
	v_add_f32_e32 v66, v178, v167
	v_exp_f32_e32 v79, v79
	v_add_f32_e32 v65, 0, v65
	v_add_f32_e32 v64, v66, v64
	v_add_f32_e32 v66, v176, v184
	v_add_f32_e32 v65, v66, v65
	v_add_f32_e32 v66, v174, v187
	v_exp_f32_e32 v165, v68
	v_exp_f32_e32 v166, v69
	v_exp_f32_e32 v185, v72
	v_exp_f32_e32 v186, v73
	v_exp_f32_e32 v189, v76
	v_exp_f32_e32 v190, v77
	v_add_f32_e32 v64, v66, v64
	v_add_f32_e32 v66, v172, v188
	v_add_f32_e32 v65, v66, v65
	v_add_f32_e32 v66, v170, v191
	v_add_f32_e32 v64, v66, v64
	v_add_f32_e32 v66, v168, v79
	v_add_f32_e32 v65, v66, v65
	v_add_f32_e32 v192, v183, v160
	v_add_f32_e32 v193, v181, v162
	v_add_f32_e32 v194, v179, v165
	v_add_f32_e32 v195, v177, v166
	v_add_f32_e32 v196, v175, v185
	v_add_f32_e32 v197, v173, v186
	v_add_f32_e32 v198, v171, v189
	v_add_f32_e32 v199, v169, v190
	v_add_f32_e32 v200, v65, v64
	v_cvt_pk_bf16_f32 v64, v183, v181
	v_cvt_pk_bf16_f32 v65, v182, v180
	v_cvt_pk_bf16_f32 v66, v179, v177
	v_cvt_pk_bf16_f32 v67, v178, v176
	v_cvt_pk_bf16_f32 v68, v175, v173
	v_cvt_pk_bf16_f32 v69, v174, v172
	v_cvt_pk_bf16_f32 v70, v171, v169
	v_cvt_pk_bf16_f32 v71, v170, v168
	s_nop 0
	v_permlane32_swap_b32_e32 v64, v66
	v_permlane32_swap_b32_e32 v65, v67
	v_permlane32_swap_b32_e32 v68, v70
	v_permlane32_swap_b32_e32 v69, v71
	v_cvt_pk_bf16_f32 v72, v160, v162
	v_cvt_pk_bf16_f32 v73, v163, v164
	v_cvt_pk_bf16_f32 v74, v165, v166
	v_cvt_pk_bf16_f32 v75, v167, v184
	v_cvt_pk_bf16_f32 v76, v185, v186
	v_cvt_pk_bf16_f32 v77, v187, v188
	v_cvt_pk_bf16_f32 v78, v189, v190
	v_cvt_pk_bf16_f32 v79, v191, v79
	s_nop 0
	v_permlane32_swap_b32_e32 v72, v74
	v_permlane32_swap_b32_e32 v73, v75
	v_permlane32_swap_b32_e32 v76, v78
	v_permlane32_swap_b32_e32 v77, v79
	ds_read_b64_tr_b16 v[162:163], v228 offset:0
	ds_read_b64_tr_b16 v[164:165], v228 offset:0x800
	ds_read_b64_tr_b16 v[166:167], v228 offset:0x1000
	ds_read_b64_tr_b16 v[168:169], v228 offset:0x1800
	ds_read_b64_tr_b16 v[170:171], v228 offset:0x2000
	ds_read_b64_tr_b16 v[172:173], v228 offset:0x2800
	ds_read_b64_tr_b16 v[174:175], v228 offset:0x3000
	ds_read_b64_tr_b16 v[176:177], v228 offset:0x3800
	s_waitcnt lgkmcnt(0)
; #define WBAR0() do { asm volatile("s_waitcnt vmcnt(0)" ::: "memory"); __syncthreads(); } while (0)
; #define EXPH(P) do { _Pragma("unroll") for (int r = 0; r < 16; ++r) P[r] = __builtin_amdgcn_exp2f(P[r]); } while (0)
;     ...
;     pv_d0(o, vb0, pa0, pa1, pa2, pa3);
;     if (!isY) { EXPH(pB0); }
;     WBAR0();
	s_nop 0
	v_mfma_f32_32x32x16_bf16 v[0:15], v[64:67], v[162:165], v[0:15]
	ds_read_b64_tr_b16 v[162:163], v228 offset:0x200
	ds_read_b64_tr_b16 v[164:165], v228 offset:0xa00
	v_mfma_f32_32x32x16_bf16 v[0:15], v[68:71], v[166:169], v[0:15]
	ds_read_b64_tr_b16 v[166:167], v228 offset:0x1200
	ds_read_b64_tr_b16 v[168:169], v228 offset:0x1a00
	v_mfma_f32_32x32x16_bf16 v[0:15], v[72:75], v[170:173], v[0:15]
	ds_read_b64_tr_b16 v[170:171], v228 offset:0x2200
	ds_read_b64_tr_b16 v[172:173], v228 offset:0x2a00
	ds_read_b64_tr_b16 v[178:179], v228 offset:0x3200
	ds_read_b64_tr_b16 v[180:181], v228 offset:0x3a00
	s_waitcnt lgkmcnt(0)
	v_mfma_f32_32x32x16_bf16 v[0:15], v[76:79], v[174:177], v[0:15]
	v_mfma_f32_32x32x16_bf16 v[16:31], v[64:67], v[162:165], v[16:31]
	ds_read_b64_tr_b16 v[162:163], v228 offset:0x400
	ds_read_b64_tr_b16 v[164:165], v228 offset:0xc00
	v_mfma_f32_32x32x16_bf16 v[16:31], v[68:71], v[166:169], v[16:31]
	ds_read_b64_tr_b16 v[166:167], v228 offset:0x1400
	ds_read_b64_tr_b16 v[168:169], v228 offset:0x1c00
	v_mfma_f32_32x32x16_bf16 v[16:31], v[72:75], v[170:173], v[16:31]
	ds_read_b64_tr_b16 v[170:171], v228 offset:0x2400
	ds_read_b64_tr_b16 v[172:173], v228 offset:0x2c00
	ds_read_b64_tr_b16 v[174:175], v228 offset:0x3400
	ds_read_b64_tr_b16 v[176:177], v228 offset:0x3c00
	s_waitcnt lgkmcnt(0)
	v_mfma_f32_32x32x16_bf16 v[16:31], v[76:79], v[178:181], v[16:31]
	v_mfma_f32_32x32x16_bf16 v[32:47], v[64:67], v[162:165], v[32:47]
	ds_read_b64_tr_b16 v[162:163], v228 offset:0x600
	ds_read_b64_tr_b16 v[164:165], v228 offset:0xe00
	v_mfma_f32_32x32x16_bf16 v[32:47], v[68:71], v[166:169], v[32:47]
	ds_read_b64_tr_b16 v[166:167], v228 offset:0x1600
	ds_read_b64_tr_b16 v[168:169], v228 offset:0x1e00
	v_mfma_f32_32x32x16_bf16 v[32:47], v[72:75], v[170:173], v[32:47]
	ds_read_b64_tr_b16 v[170:171], v228 offset:0x2600
	ds_read_b64_tr_b16 v[172:173], v228 offset:0x2e00
	ds_read_b64_tr_b16 v[178:179], v228 offset:0x3600
	ds_read_b64_tr_b16 v[180:181], v228 offset:0x3e00
	s_waitcnt lgkmcnt(0)
	v_mfma_f32_32x32x16_bf16 v[32:47], v[76:79], v[174:177], v[32:47]
	v_mfma_f32_32x32x16_bf16 v[48:63], v[64:67], v[162:165], v[48:63]
	s_waitcnt vmcnt(0)
	v_exp_f32_e32 v80, v80
	v_exp_f32_e32 v81, v81
	v_exp_f32_e32 v82, v82
	v_exp_f32_e32 v83, v83
	v_exp_f32_e32 v84, v84
	v_exp_f32_e32 v85, v85
	v_mfma_f32_32x32x16_bf16 v[48:63], v[68:71], v[166:169], v[48:63]
	v_exp_f32_e32 v86, v86
	v_exp_f32_e32 v87, v87
	v_exp_f32_e32 v88, v88
	v_exp_f32_e32 v89, v89
	v_exp_f32_e32 v90, v90
	v_exp_f32_e32 v91, v91
	v_exp_f32_e32 v92, v92
	v_mfma_f32_32x32x16_bf16 v[48:63], v[72:75], v[170:173], v[48:63]
	v_exp_f32_e32 v93, v93
	v_exp_f32_e32 v94, v94
	v_exp_f32_e32 v95, v95
	s_waitcnt lgkmcnt(0)
	s_barrier
; #define SBAR() __builtin_amdgcn_sched_barrier(0)
; #define EXPH(P) do { _Pragma("unroll") for (int r = 0; r < 16; ++r) P[r] = __builtin_amdgcn_exp2f(P[r]); } while (0)
;     ...
;     if (isY) { EXPH(pB0); }
;     SBAR(); finishSM<true>(pB0, pB1, dummy_a, l_reg, pa0, pa1, pa2, pa3); SBAR();
;     pv_d0(o, vb0 + SHM_V, pa0, pa1, pa2, pa3);
;     __builtin_amdgcn_s_setprio(0);
;     (void)dummy_m;
;     { auto rr = __builtin_amdgcn_permlane32_swap(__float_as_uint(l_reg), __float_as_uint(l_reg), false, false); l_reg = __uint_as_float(rr[0]) + __uint_as_float(rr[1]); }
;     {
;         int t2 = threadIdx.x; asm volatile("" : "+v"(t2));
;         const int wid2 = t2 >> 6, lane2 = t2 & 63, r32b = lane2 & 31, hib = lane2 >> 5;
;         float* li2 = (float*)(lds + OFF_WS) + wid2 * 64;
;         if (hib == 0) li2[r32b] = l_reg; asm volatile("s_waitcnt lgkmcnt(0)" ::: "memory");
	v_mfma_f32_32x32x16_bf16 v[48:63], v[76:79], v[178:181], v[48:63]
	v_mfma_f32_32x32x16_bf16 v[64:79], v[144:147], v[116:119], 0
	v_mfma_f32_32x32x16_bf16 v[64:79], v[148:151], v[112:115], v[64:79]
	v_mfma_f32_32x32x16_bf16 v[64:79], v[152:155], v[108:111], v[64:79]
	v_mfma_f32_32x32x16_bf16 v[64:79], v[156:159], v[104:107], v[64:79]
	v_mfma_f32_32x32x16_bf16 v[64:79], v[140:143], v[100:103], v[64:79]
	v_mfma_f32_32x32x16_bf16 v[64:79], v[136:139], v[96:99], v[64:79]
	v_add_f32_e32 v96, 0, v192
	v_add_f32_e32 v97, 0, v193
	v_add_f32_e32 v96, v194, v96
	v_add_f32_e32 v97, v195, v97
	v_add_f32_e32 v96, v196, v96
	v_add_f32_e32 v97, v197, v97
	v_add_f32_e32 v96, v198, v96
	v_mfma_f32_32x32x16_bf16 v[64:79], v[132:135], v[124:127], v[64:79]
	v_add_f32_e32 v97, v199, v97
	v_add_f32_e32 v96, v97, v96
	v_add_f32_e32 v96, v200, v96
	v_add_f32_e32 v96, v230, v96
	v_mfma_f32_32x32x16_bf16 v[64:79], v[128:131], v[120:123], v[64:79]
	s_nop 11
	v_exp_f32_e32 v64, v64
	v_exp_f32_e32 v65, v65
	v_exp_f32_e32 v98, v68
	v_exp_f32_e32 v97, v66
	v_exp_f32_e32 v99, v69
	v_exp_f32_e32 v67, v67
	v_exp_f32_e32 v100, v70
	v_exp_f32_e32 v101, v71
	v_add_f32_e32 v66, v80, v64
	v_exp_f32_e32 v102, v72
	v_add_f32_e32 v66, 0, v66
	v_add_f32_e32 v68, v81, v65
	v_add_f32_e32 v71, v84, v98
	v_exp_f32_e32 v103, v73
	v_add_f32_e32 v68, 0, v68
	v_add_f32_e32 v69, v82, v97
	v_add_f32_e32 v66, v71, v66
	v_add_f32_e32 v71, v85, v99
	v_exp_f32_e32 v104, v74
	v_add_f32_e32 v69, 0, v69
	v_add_f32_e32 v70, v83, v67
	v_add_f32_e32 v68, v71, v68
	v_add_f32_e32 v71, v86, v100
	v_exp_f32_e32 v105, v75
	v_add_f32_e32 v70, 0, v70
	v_add_f32_e32 v69, v71, v69
	v_add_f32_e32 v71, v87, v101
	v_exp_f32_e32 v106, v76
	v_add_f32_e32 v70, v71, v70
	v_add_f32_e32 v71, v88, v102
	v_exp_f32_e32 v107, v77
	v_add_f32_e32 v66, v71, v66
	v_add_f32_e32 v71, v89, v103
	v_exp_f32_e32 v108, v78
	v_add_f32_e32 v68, v71, v68
	v_add_f32_e32 v71, v90, v104
	v_exp_f32_e32 v109, v79
	v_add_f32_e32 v69, v71, v69
	v_add_f32_e32 v71, v91, v105
	v_add_f32_e32 v70, v71, v70
	v_add_f32_e32 v71, v92, v106
	v_add_f32_e32 v66, v71, v66
	v_add_f32_e32 v71, v93, v107
	v_add_f32_e32 v68, v71, v68
	v_add_f32_e32 v71, v94, v108
	v_add_f32_e32 v69, v71, v69
	v_add_f32_e32 v71, v95, v109
	v_add_f32_e32 v70, v71, v70
	v_add_f32_e32 v66, v68, v66
	v_add_f32_e32 v68, v70, v69
	v_add_f32_e32 v66, v68, v66
	v_cvt_pk_bf16_f32 v68, v80, v81
	v_cvt_pk_bf16_f32 v69, v82, v83
	v_cvt_pk_bf16_f32 v70, v84, v85
	v_cvt_pk_bf16_f32 v71, v86, v87
	v_add_f32_e32 v66, v96, v66
	v_permlane32_swap_b32_e32 v68, v70
	v_permlane32_swap_b32_e32 v69, v71
	v_cvt_pk_bf16_f32 v72, v88, v89
	v_cvt_pk_bf16_f32 v73, v90, v91
	v_cvt_pk_bf16_f32 v74, v92, v93
	v_cvt_pk_bf16_f32 v75, v94, v95
	v_cvt_pk_bf16_f32 v76, v64, v65
	v_cvt_pk_bf16_f32 v77, v97, v67
	v_cvt_pk_bf16_f32 v78, v98, v99
	v_cvt_pk_bf16_f32 v79, v100, v101
	v_cvt_pk_bf16_f32 v80, v102, v103
	v_cvt_pk_bf16_f32 v81, v104, v105
	v_cvt_pk_bf16_f32 v82, v106, v107
	v_cvt_pk_bf16_f32 v83, v108, v109
	s_nop 0
	v_permlane32_swap_b32_e32 v72, v74
	v_permlane32_swap_b32_e32 v73, v75
	v_permlane32_swap_b32_e32 v76, v78
	v_permlane32_swap_b32_e32 v77, v79
	v_permlane32_swap_b32_e32 v80, v82
	v_permlane32_swap_b32_e32 v81, v83
	ds_read_b64_tr_b16 v[84:85], v227 offset:0
	ds_read_b64_tr_b16 v[86:87], v227 offset:0x800
	ds_read_b64_tr_b16 v[88:89], v227 offset:0x1000
	ds_read_b64_tr_b16 v[90:91], v227 offset:0x1800
	ds_read_b64_tr_b16 v[92:93], v227 offset:0x2000
	ds_read_b64_tr_b16 v[94:95], v227 offset:0x2800
	ds_read_b64_tr_b16 v[96:97], v227 offset:0x3000
	ds_read_b64_tr_b16 v[98:99], v227 offset:0x3800
	s_waitcnt lgkmcnt(0)
	s_nop 0
	v_mfma_f32_32x32x16_bf16 v[0:15], v[68:71], v[84:87], v[0:15]
	ds_read_b64_tr_b16 v[84:85], v227 offset:0x200
	ds_read_b64_tr_b16 v[86:87], v227 offset:0xa00
	v_mfma_f32_32x32x16_bf16 v[0:15], v[72:75], v[88:91], v[0:15]
	ds_read_b64_tr_b16 v[88:89], v227 offset:0x1200
	ds_read_b64_tr_b16 v[90:91], v227 offset:0x1a00
	v_mfma_f32_32x32x16_bf16 v[0:15], v[76:79], v[92:95], v[0:15]
	ds_read_b64_tr_b16 v[92:93], v227 offset:0x2200
	ds_read_b64_tr_b16 v[94:95], v227 offset:0x2a00
	ds_read_b64_tr_b16 v[100:101], v227 offset:0x3200
	ds_read_b64_tr_b16 v[102:103], v227 offset:0x3a00
	s_waitcnt lgkmcnt(0)
	v_mfma_f32_32x32x16_bf16 v[0:15], v[80:83], v[96:99], v[0:15]
	v_mfma_f32_32x32x16_bf16 v[16:31], v[68:71], v[84:87], v[16:31]
	ds_read_b64_tr_b16 v[84:85], v227 offset:0x400
	ds_read_b64_tr_b16 v[86:87], v227 offset:0xc00
	v_mfma_f32_32x32x16_bf16 v[16:31], v[72:75], v[88:91], v[16:31]
	ds_read_b64_tr_b16 v[88:89], v227 offset:0x1400
	ds_read_b64_tr_b16 v[90:91], v227 offset:0x1c00
	v_mfma_f32_32x32x16_bf16 v[16:31], v[76:79], v[92:95], v[16:31]
	ds_read_b64_tr_b16 v[92:93], v227 offset:0x2400
	ds_read_b64_tr_b16 v[94:95], v227 offset:0x2c00
	ds_read_b64_tr_b16 v[96:97], v227 offset:0x3400
	ds_read_b64_tr_b16 v[98:99], v227 offset:0x3c00
	s_waitcnt lgkmcnt(0)
	v_mfma_f32_32x32x16_bf16 v[16:31], v[80:83], v[100:103], v[16:31]
	v_mfma_f32_32x32x16_bf16 v[32:47], v[68:71], v[84:87], v[32:47]
	ds_read_b64_tr_b16 v[84:85], v227 offset:0x600
	ds_read_b64_tr_b16 v[86:87], v227 offset:0xe00
	v_mfma_f32_32x32x16_bf16 v[32:47], v[72:75], v[88:91], v[32:47]
	ds_read_b64_tr_b16 v[88:89], v227 offset:0x1600
	ds_read_b64_tr_b16 v[90:91], v227 offset:0x1e00
	v_mfma_f32_32x32x16_bf16 v[32:47], v[76:79], v[92:95], v[32:47]
	ds_read_b64_tr_b16 v[92:93], v227 offset:0x2600
	ds_read_b64_tr_b16 v[94:95], v227 offset:0x2e00
	ds_read_b64_tr_b16 v[100:101], v227 offset:0x3600
	ds_read_b64_tr_b16 v[102:103], v227 offset:0x3e00
	s_waitcnt lgkmcnt(0)
	v_mfma_f32_32x32x16_bf16 v[32:47], v[80:83], v[96:99], v[32:47]
	v_mfma_f32_32x32x16_bf16 v[48:63], v[68:71], v[84:87], v[48:63]
	v_mfma_f32_32x32x16_bf16 v[48:63], v[72:75], v[88:91], v[48:63]
	v_mfma_f32_32x32x16_bf16 v[48:63], v[76:79], v[92:95], v[48:63]
	v_mfma_f32_32x32x16_bf16 v[48:63], v[80:83], v[100:103], v[48:63]
	s_setprio 0
	v_mov_b32_e32 v64, v218
	v_mov_b32_e32 v69, v66
	s_nop 1
	v_permlane32_swap_b32_e32 v66, v69
	v_and_b32_e32 v65, 63, v64
	v_and_b32_e32 v68, 0x3fffffc0, v64
	v_and_b32_e32 v67, 31, v64
	v_lshl_add_u32 v68, v68, 2, s50
	v_cmp_gt_u32_e32 vcc, 32, v65
	s_and_saveexec_b64 s[0:1], vcc
	s_cbranch_execz .LBB0_525
	v_add_f32_e32 v66, v66, v69
	v_lshl_add_u32 v69, v67, 2, v68
	ds_write_b32 v69, v66
	s_branch .LBB0_525

; __global__ void __launch_bounds__(NTHREADS, 2) fwd_kernel(Args a) {
;     extern __shared__ __attribute__((aligned(16))) unsigned char lds[];
	.amdhsa_kernel _Z10fwd_kernel4Args
		.amdhsa_group_segment_fixed_size 0
		.amdhsa_private_segment_fixed_size 0
		.amdhsa_kernarg_size 472
		.amdhsa_user_sgpr_count 2
		.amdhsa_user_sgpr_dispatch_ptr 0
		.amdhsa_user_sgpr_queue_ptr 0
		.amdhsa_user_sgpr_kernarg_segment_ptr 1
		.amdhsa_user_sgpr_dispatch_id 0
		.amdhsa_user_sgpr_kernarg_preload_length 0
		.amdhsa_user_sgpr_kernarg_preload_offset 0
		.amdhsa_user_sgpr_private_segment_size 0
		.amdhsa_uses_dynamic_stack 0
		.amdhsa_enable_private_segment 0
		.amdhsa_system_sgpr_workgroup_id_x 1
		.amdhsa_system_sgpr_workgroup_id_y 0
		.amdhsa_system_sgpr_workgroup_id_z 0
		.amdhsa_system_sgpr_workgroup_info 0
		.amdhsa_system_vgpr_workitem_id 2
		.amdhsa_next_free_vgpr 253
		.amdhsa_next_free_sgpr 102
		.amdhsa_accum_offset 256
		.amdhsa_reserve_vcc 1
		.amdhsa_float_round_mode_32 0
		.amdhsa_float_round_mode_16_64 0
		.amdhsa_float_denorm_mode_32 3
		.amdhsa_float_denorm_mode_16_64 3
		.amdhsa_dx10_clamp 1
		.amdhsa_ieee_mode 1
		.amdhsa_fp16_overflow 0
		.amdhsa_tg_split 0
		.amdhsa_exception_fp_ieee_invalid_op 0
		.amdhsa_exception_fp_denorm_src 0
		.amdhsa_exception_fp_ieee_div_zero 0
		.amdhsa_exception_fp_ieee_overflow 0
		.amdhsa_exception_fp_ieee_underflow 0
		.amdhsa_exception_fp_ieee_inexact 0
		.amdhsa_exception_int_div_zero 0
	.end_amdhsa_kernel

; __global__ void __launch_bounds__(NTHREADS, 2) fwd_kernel(Args a) {
;     extern __shared__ __attribute__((aligned(16))) unsigned char lds[];
amdhsa.kernels:
  - .agpr_count:     0
    .args:
      - .offset:         0
        .size:           216
        .value_kind:     by_value
      - .offset:         216
        .size:           4
        .value_kind:     hidden_block_count_x
      - .offset:         220
        .size:           4
        .value_kind:     hidden_block_count_y
      - .offset:         224
        .size:           4
        .value_kind:     hidden_block_count_z
      - .offset:         228
        .size:           2
        .value_kind:     hidden_group_size_x
      - .offset:         230
        .size:           2
        .value_kind:     hidden_group_size_y
      - .offset:         232
        .size:           2
        .value_kind:     hidden_group_size_z
      - .offset:         234
        .size:           2
        .value_kind:     hidden_remainder_x
      - .offset:         236
        .size:           2
        .value_kind:     hidden_remainder_y
      - .offset:         238
        .size:           2
        .value_kind:     hidden_remainder_z
      - .offset:         256
        .size:           8
        .value_kind:     hidden_global_offset_x
      - .offset:         264
        .size:           8
        .value_kind:     hidden_global_offset_y
      - .offset:         272
        .size:           8
        .value_kind:     hidden_global_offset_z
      - .offset:         280
        .size:           2
        .value_kind:     hidden_grid_dims
      - .offset:         304
        .size:           8
        .value_kind:     hidden_multigrid_sync_arg
      - .offset:         336
        .size:           4
        .value_kind:     hidden_dynamic_lds_size
    .group_segment_fixed_size: 0
    .kernarg_segment_align: 8
    .kernarg_segment_size: 472
    .language:       OpenCL C
    .language_version:
      - 2
      - 0
    .max_flat_workgroup_size: 512
    .name:           _Z10fwd_kernel4Args
    .private_segment_fixed_size: 0
    .sgpr_count:     108
    .sgpr_spill_count: 31
    .symbol:         _Z10fwd_kernel4Args.kd
    .uniform_work_group_size: 1
    .uses_dynamic_stack: false
    .vgpr_count:     253
    .vgpr_spill_count: 0
    .wavefront_size: 64
